# attention: K/V tile prefetch DMAs issued unguarded (reads past the last tile land in unused LDS; saves two scalar instructions per piece in the QK gaps)
# baseline (speedup 1.0000x reference)
; __device__ __forceinline__ float fast_exp2(float x) { return __builtin_amdgcn_exp2f(x); }
; __device__ __forceinline__ void attn_phase(int wv, const bf16_t* Q, const bf16_t* Kf, const bf16_t* Vt, const bf16_t* proj, bf16_t* mixed, LAS unsigned char* lds) { LIDS
;     ...
;                     for (int kb = 0; kb < 2; ++kb)
; #pragma unroll
;                         for (int j = 0; j < 16; ++j) s[kb][j] = zf;
;                     unsigned kad[4];
; #pragma unroll
;                     for (int kl = 0; kl < 4; ++kl) kad[kl] = (unsigned)(size_t)kb_ + (unsigned)koffl[kl];
;                     bf16x8 fr_[4];
;     ...
;                     ATT_KRD(0); ATT_KRD(1); ATT_KRD(2); ATT_KRD(3);
; #pragma unroll
;                     for (int i = 0; i < 24; ++i) {
;                         LGK(i < 21 ? 3 : 23 - i, fr_[i & 3]);
;                         s[i & 1] = __builtin_amdgcn_mfma_f32_32x32x16_bf16(fr_[i & 3], qf[i >> 1], s[i & 1], 0, 0, 0);
;                         if (i + 4 < 24) ATT_KRD(i + 4);
;                     }
;     ...
;                     unsigned vad[4];
; #pragma unroll
;                     for (int c = 0; c < 4; ++c) vad[c] = (unsigned)(size_t)vb_ + (unsigned)voffl[c];
;     ...
;                     ATT_VRD(0); ATT_VRD(1); ATT_VRD(2); ATT_VRD(3);
;                     if (64 * t + 63 > qw0) {
; #pragma unroll
;                         for (int kb = 0; kb < 2; ++kb)
; #pragma unroll
;                             for (int j = 0; j < 16; ++j) { const int key = 64 * t + 32 * kb + 16 * (j >> 3) + 8 * h + (j & 7); if (key > q) s[kb][j] = -1e30f; }
;                     }
;                     float mx = -1e30f;
; #pragma unroll
;                     for (int kb = 0; kb < 2; ++kb)
; #pragma unroll
;                         for (int j = 0; j < 16; ++j) mx = fmaxf(mx, s[kb][j]);
;                     mx = fmaxf(mx, __shfl_xor(mx, 32));
;                     if (__builtin_amdgcn_ballot_w64(mx > mrun + 8.0f) != 0ull) {
;                         const float mnew = fmaxf(mrun, mx), alpha = fast_exp2(mrun - mnew); mrun = mnew;
;                         lsum *= alpha;
; #pragma unroll
;                         for (int bb = 0; bb < 4; ++bb)
; #pragma unroll
;                             for (int j = 0; j < 16; ++j) o[bb][j] *= alpha;
;                     }
;                     float ps = 0.f;
; #pragma unroll
;                     for (int kb = 0; kb < 2; ++kb)
; #pragma unroll
.Lp2_top0:
	s_waitcnt lgkmcnt(3)
	v_mfma_f32_32x32x16_bf16 v[228:243], v[160:163], v[112:115], v[0:15]
	ds_read_b128 v[160:163], v209 offset:0xa010
	v_exp_f32_e32 v96, v96
	v_exp_f32_e32 v97, v97
	s_nop 0
	v_add_f32_e32 v246, v96, v97
	s_waitcnt lgkmcnt(3)
	v_mfma_f32_32x32x16_bf16 v[178:193], v[164:167], v[112:115], v[0:15]
	ds_read_b128 v[164:167], v209 offset:0xd010
	v_cvt_pk_bf16_f32 v96, v96, v97
	v_exp_f32_e32 v98, v98
	v_exp_f32_e32 v99, v99
	s_mov_b32 m0, s58
	s_nop 0
	global_load_lds_dwordx4 v176, s[62:63]
	s_waitcnt lgkmcnt(3)
	v_mfma_f32_32x32x16_bf16 v[228:243], v[168:171], v[116:119], v[228:243]
	ds_read_b128 v[168:171], v217 offset:0xa010
	v_add_f32_e32 v246, v246, v98
	v_add_f32_e32 v246, v246, v99
	v_cvt_pk_bf16_f32 v97, v98, v99
	v_exp_f32_e32 v100, v100
	s_waitcnt lgkmcnt(3)
	v_mfma_f32_32x32x16_bf16 v[178:193], v[172:175], v[116:119], v[178:193]
	ds_read_b128 v[172:175], v217 offset:0xd010
	v_exp_f32_e32 v101, v101
	v_add_f32_e32 v246, v246, v100
	v_add_f32_e32 v246, v246, v101
	v_cvt_pk_bf16_f32 v98, v100, v101
	s_waitcnt lgkmcnt(3)
	v_mfma_f32_32x32x16_bf16 v[228:243], v[160:163], v[120:123], v[228:243]
	ds_read_b128 v[160:163], v207 offset:0xa090
	v_exp_f32_e32 v102, v102
	v_exp_f32_e32 v103, v103
	v_add_f32_e32 v246, v246, v102
	s_waitcnt lgkmcnt(3)
	v_mfma_f32_32x32x16_bf16 v[178:193], v[164:167], v[120:123], v[178:193]
	ds_read_b128 v[164:167], v207 offset:0xd090
	v_add_f32_e32 v246, v246, v103
	v_cvt_pk_bf16_f32 v99, v102, v103
	v_exp_f32_e32 v104, v104
	s_add_i32 m0, s58, 0x2000
	s_nop 0
	global_load_lds_dwordx4 v194, s[62:63]
	s_waitcnt lgkmcnt(3)
	v_mfma_f32_32x32x16_bf16 v[228:243], v[168:171], v[124:127], v[228:243]
	ds_read_b128 v[168:171], v208 offset:0xa090
	v_exp_f32_e32 v105, v105
	v_add_f32_e32 v246, v246, v104
	v_add_f32_e32 v246, v246, v105
	v_cvt_pk_bf16_f32 v100, v104, v105
	s_waitcnt lgkmcnt(3)
	v_mfma_f32_32x32x16_bf16 v[178:193], v[172:175], v[124:127], v[178:193]
	ds_read_b128 v[172:175], v208 offset:0xd090
	v_exp_f32_e32 v106, v106
	v_exp_f32_e32 v107, v107
	v_add_f32_e32 v246, v246, v106
	s_waitcnt lgkmcnt(3)
	v_mfma_f32_32x32x16_bf16 v[228:243], v[160:163], v[128:131], v[228:243]
	ds_read_b128 v[160:163], v209 offset:0xa090
	v_add_f32_e32 v246, v246, v107
	v_cvt_pk_bf16_f32 v101, v106, v107
	v_exp_f32_e32 v108, v108
	s_waitcnt lgkmcnt(3)
	v_mfma_f32_32x32x16_bf16 v[178:193], v[164:167], v[128:131], v[178:193]
	ds_read_b128 v[164:167], v209 offset:0xd090
	v_exp_f32_e32 v109, v109
	v_add_f32_e32 v246, v246, v108
	v_add_f32_e32 v246, v246, v109
	v_cvt_pk_bf16_f32 v102, v108, v109
	s_add_i32 m0, s58, 0x4000
	s_nop 0
	global_load_lds_dwordx4 v196, s[62:63]
	s_waitcnt lgkmcnt(3)
	v_mfma_f32_32x32x16_bf16 v[228:243], v[168:171], v[132:135], v[228:243]
	ds_read_b128 v[168:171], v217 offset:0xa090
	v_exp_f32_e32 v110, v110
	v_exp_f32_e32 v111, v111
	v_add_f32_e32 v246, v246, v110
	s_waitcnt lgkmcnt(3)
	v_mfma_f32_32x32x16_bf16 v[178:193], v[172:175], v[132:135], v[178:193]
	ds_read_b128 v[172:175], v217 offset:0xd090
	v_add_f32_e32 v246, v246, v111
	v_cvt_pk_bf16_f32 v103, v110, v111
	v_exp_f32_e32 v80, v80
	s_waitcnt lgkmcnt(3)
	v_mfma_f32_32x32x16_bf16 v[228:243], v[160:163], v[136:139], v[228:243]
	ds_read_b128 v[160:163], v207 offset:0xa110
	v_exp_f32_e32 v81, v81
	v_add_f32_e32 v246, v246, v80
	v_add_f32_e32 v246, v246, v81
	v_cvt_pk_bf16_f32 v80, v80, v81
	s_waitcnt lgkmcnt(3)
	v_mfma_f32_32x32x16_bf16 v[178:193], v[164:167], v[136:139], v[178:193]
	ds_read_b128 v[164:167], v207 offset:0xd110
	v_exp_f32_e32 v82, v82
	v_exp_f32_e32 v83, v83
	v_add_f32_e32 v246, v246, v82
	s_add_i32 m0, s58, 0x10000
	s_nop 0
	global_load_lds_dwordx4 v198, s[72:73]
	s_waitcnt lgkmcnt(3)
	v_mfma_f32_32x32x16_bf16 v[228:243], v[168:171], v[140:143], v[228:243]
	ds_read_b128 v[168:171], v208 offset:0xa110
	v_add_f32_e32 v246, v246, v83
	v_cvt_pk_bf16_f32 v81, v82, v83
	v_exp_f32_e32 v84, v84
	s_waitcnt lgkmcnt(3)
	v_mfma_f32_32x32x16_bf16 v[178:193], v[172:175], v[140:143], v[178:193]
	ds_read_b128 v[172:175], v208 offset:0xd110
	v_exp_f32_e32 v85, v85
	v_add_f32_e32 v246, v246, v84
	v_add_f32_e32 v246, v246, v85
	v_cvt_pk_bf16_f32 v82, v84, v85
	s_waitcnt lgkmcnt(3)
	v_mfma_f32_32x32x16_bf16 v[228:243], v[160:163], v[144:147], v[228:243]
	ds_read_b128 v[160:163], v209 offset:0xa110
	v_exp_f32_e32 v86, v86
	v_exp_f32_e32 v87, v87
	v_add_f32_e32 v246, v246, v86
	s_waitcnt lgkmcnt(3)
	v_mfma_f32_32x32x16_bf16 v[178:193], v[164:167], v[144:147], v[178:193]
	ds_read_b128 v[164:167], v209 offset:0xd110
	v_add_f32_e32 v246, v246, v87
	v_cvt_pk_bf16_f32 v83, v86, v87
	v_exp_f32_e32 v88, v88
	s_add_i32 m0, s58, 0x12000
	s_nop 0
	global_load_lds_dwordx4 v200, s[72:73]
	s_waitcnt lgkmcnt(3)
	v_mfma_f32_32x32x16_bf16 v[228:243], v[168:171], v[148:151], v[228:243]
	ds_read_b128 v[168:171], v217 offset:0xa110
	v_exp_f32_e32 v89, v89
	v_add_f32_e32 v246, v246, v88
	v_add_f32_e32 v246, v246, v89
	v_cvt_pk_bf16_f32 v84, v88, v89
	s_waitcnt lgkmcnt(3)
	v_mfma_f32_32x32x16_bf16 v[178:193], v[172:175], v[148:151], v[178:193]
	ds_read_b128 v[172:175], v217 offset:0xd110
	v_exp_f32_e32 v90, v90
	v_exp_f32_e32 v91, v91
	v_add_f32_e32 v246, v246, v90
	s_waitcnt lgkmcnt(3)
	v_mfma_f32_32x32x16_bf16 v[228:243], v[160:163], v[152:155], v[228:243]
	ds_read_b128 v[160:163], v218 offset:0x6010
	v_add_f32_e32 v246, v246, v91
	v_cvt_pk_bf16_f32 v85, v90, v91
	v_exp_f32_e32 v92, v92
	s_waitcnt lgkmcnt(3)
	v_mfma_f32_32x32x16_bf16 v[178:193], v[164:167], v[152:155], v[178:193]
	ds_read_b128 v[164:167], v218 offset:0x7010
	v_exp_f32_e32 v93, v93
	v_add_f32_e32 v246, v246, v92
	v_add_f32_e32 v246, v246, v93
	v_cvt_pk_bf16_f32 v86, v92, v93
	s_waitcnt lgkmcnt(3)
	v_mfma_f32_32x32x16_bf16 v[228:243], v[168:171], v[156:159], v[228:243]
	ds_read_b128 v[168:171], v218 offset:0x8010
	v_exp_f32_e32 v94, v94
	v_exp_f32_e32 v95, v95
	v_add_f32_e32 v246, v246, v94
	s_waitcnt lgkmcnt(3)
	v_mfma_f32_32x32x16_bf16 v[178:193], v[172:175], v[156:159], v[178:193]
	ds_read_b128 v[172:175], v218 offset:0x9010
	v_add_f32_e32 v246, v246, v95
	v_cvt_pk_bf16_f32 v87, v94, v95
	v_add_f32_e32 v224, v224, v246
	s_waitcnt lgkmcnt(3)
	v_mfma_f32_32x32x16_bf16 v[48:63], v[160:163], v[96:99], v[48:63]
	ds_read_b128 v[160:163], v219 offset:0x6010
	s_waitcnt lgkmcnt(3)
	v_mfma_f32_32x32x16_bf16 v[32:47], v[164:167], v[96:99], v[32:47]
	ds_read_b128 v[164:167], v219 offset:0x7010
	s_waitcnt lgkmcnt(3)
	v_mfma_f32_32x32x16_bf16 v[16:31], v[168:171], v[96:99], v[16:31]
	ds_read_b128 v[168:171], v219 offset:0x8010
	s_waitcnt lgkmcnt(3)
	v_mfma_f32_32x32x16_bf16 v[64:79], v[172:175], v[96:99], v[64:79]
	ds_read_b128 v[172:175], v219 offset:0x9010
	s_cmp_lg_u32 s24, s21
	s_cbranch_scc1 .Lp2_nomask2
; __device__ __forceinline__ void attn_phase(int wv, const bf16_t* Q, const bf16_t* Kf, const bf16_t* Vt, const bf16_t* proj, bf16_t* mixed, LAS unsigned char* lds) { LIDS
;     ...
;                     if (64 * t + 63 > qw0) {
; #pragma unroll
;                         for (int kb = 0; kb < 2; ++kb)
; #pragma unroll
;                             for (int j = 0; j < 16; ++j) { const int key = 64 * t + 32 * kb + 16 * (j >> 3) + 8 * h + (j & 7); if (key > q) s[kb][j] = -1e30f; }
;                     }
	s_lshl_b32 s23, s21, 6
	v_add_u32_e32 v244, s23, v222
	v_sub_u32_e32 v244, v223, v244
	v_cmp_le_i32_e32 vcc, 0, v244
	s_nop 1
	v_cndmask_b32_e32 v228, v215, v228, vcc
	v_cmp_le_i32_e32 vcc, 1, v244
	s_nop 1
	v_cndmask_b32_e32 v229, v215, v229, vcc
	v_cmp_le_i32_e32 vcc, 2, v244
	s_nop 1
	v_cndmask_b32_e32 v230, v215, v230, vcc
	v_cmp_le_i32_e32 vcc, 3, v244
	s_nop 1
	v_cndmask_b32_e32 v231, v215, v231, vcc
	v_cmp_le_i32_e32 vcc, 4, v244
	s_nop 1
	v_cndmask_b32_e32 v232, v215, v232, vcc
	v_cmp_le_i32_e32 vcc, 5, v244
	s_nop 1
	v_cndmask_b32_e32 v233, v215, v233, vcc
	v_cmp_le_i32_e32 vcc, 6, v244
	s_nop 1
	v_cndmask_b32_e32 v234, v215, v234, vcc
	v_cmp_le_i32_e32 vcc, 7, v244
	s_nop 1
	v_cndmask_b32_e32 v235, v215, v235, vcc
	v_cmp_le_i32_e32 vcc, 16, v244
	s_nop 1
	v_cndmask_b32_e32 v236, v215, v236, vcc
	v_cmp_le_i32_e32 vcc, 17, v244
	s_nop 1
	v_cndmask_b32_e32 v237, v215, v237, vcc
	v_cmp_le_i32_e32 vcc, 18, v244
	s_nop 1
	v_cndmask_b32_e32 v238, v215, v238, vcc
	v_cmp_le_i32_e32 vcc, 19, v244
	s_nop 1
	v_cndmask_b32_e32 v239, v215, v239, vcc
	v_cmp_le_i32_e32 vcc, 20, v244
	s_nop 1
	v_cndmask_b32_e32 v240, v215, v240, vcc
	v_cmp_le_i32_e32 vcc, 21, v244
	s_nop 1
	v_cndmask_b32_e32 v241, v215, v241, vcc
	v_cmp_le_i32_e32 vcc, 22, v244
	s_nop 1
	v_cndmask_b32_e32 v242, v215, v242, vcc
	v_cmp_le_i32_e32 vcc, 23, v244
	s_nop 1
	v_cndmask_b32_e32 v243, v215, v243, vcc
	v_cmp_le_i32_e32 vcc, 32, v244
	s_nop 1
	v_cndmask_b32_e32 v178, v215, v178, vcc
	v_cmp_le_i32_e32 vcc, 33, v244
	s_nop 1
	v_cndmask_b32_e32 v179, v215, v179, vcc
	v_cmp_le_i32_e32 vcc, 34, v244
	s_nop 1
	v_cndmask_b32_e32 v180, v215, v180, vcc
	v_cmp_le_i32_e32 vcc, 35, v244
	s_nop 1
	v_cndmask_b32_e32 v181, v215, v181, vcc
	v_cmp_le_i32_e32 vcc, 36, v244
	s_nop 1
	v_cndmask_b32_e32 v182, v215, v182, vcc
	v_cmp_le_i32_e32 vcc, 37, v244
	s_nop 1
	v_cndmask_b32_e32 v183, v215, v183, vcc
	v_cmp_le_i32_e32 vcc, 38, v244
	s_nop 1
	v_cndmask_b32_e32 v184, v215, v184, vcc
	v_cmp_le_i32_e32 vcc, 39, v244
	s_nop 1
	v_cndmask_b32_e32 v185, v215, v185, vcc
	v_cmp_le_i32_e32 vcc, 48, v244
	s_nop 1
	v_cndmask_b32_e32 v186, v215, v186, vcc
	v_cmp_le_i32_e32 vcc, 49, v244
	s_nop 1
	v_cndmask_b32_e32 v187, v215, v187, vcc
	v_cmp_le_i32_e32 vcc, 50, v244
	s_nop 1
	v_cndmask_b32_e32 v188, v215, v188, vcc
	v_cmp_le_i32_e32 vcc, 51, v244
	s_nop 1
	v_cndmask_b32_e32 v189, v215, v189, vcc
	v_cmp_le_i32_e32 vcc, 52, v244
	s_nop 1
	v_cndmask_b32_e32 v190, v215, v190, vcc
	v_cmp_le_i32_e32 vcc, 53, v244
	s_nop 1
	v_cndmask_b32_e32 v191, v215, v191, vcc
	v_cmp_le_i32_e32 vcc, 54, v244
	s_nop 1
	v_cndmask_b32_e32 v192, v215, v192, vcc
	v_cmp_le_i32_e32 vcc, 55, v244
	s_nop 1
	v_cndmask_b32_e32 v193, v215, v193, vcc

; __device__ __forceinline__ float fast_exp2(float x) { return __builtin_amdgcn_exp2f(x); }
; __device__ __forceinline__ void attn_phase(int wv, const bf16_t* Q, const bf16_t* Kf, const bf16_t* Vt, const bf16_t* proj, bf16_t* mixed, LAS unsigned char* lds) { LIDS
;     ...
;                     for (int kb = 0; kb < 2; ++kb)
; #pragma unroll
;                         for (int j = 0; j < 16; ++j) s[kb][j] = zf;
;                     unsigned kad[4];
; #pragma unroll
;                     for (int kl = 0; kl < 4; ++kl) kad[kl] = (unsigned)(size_t)kb_ + (unsigned)koffl[kl];
;                     bf16x8 fr_[4];
;     ...
;                     ATT_KRD(0); ATT_KRD(1); ATT_KRD(2); ATT_KRD(3);
; #pragma unroll
;                     for (int i = 0; i < 24; ++i) {
;                         LGK(i < 21 ? 3 : 23 - i, fr_[i & 3]);
;                         s[i & 1] = __builtin_amdgcn_mfma_f32_32x32x16_bf16(fr_[i & 3], qf[i >> 1], s[i & 1], 0, 0, 0);
;                         if (i + 4 < 24) ATT_KRD(i + 4);
;                     }
;     ...
;                     unsigned vad[4];
; #pragma unroll
;                     for (int c = 0; c < 4; ++c) vad[c] = (unsigned)(size_t)vb_ + (unsigned)voffl[c];
;     ...
;                     ATT_VRD(0); ATT_VRD(1); ATT_VRD(2); ATT_VRD(3);
;                     if (64 * t + 63 > qw0) {
; #pragma unroll
;                         for (int kb = 0; kb < 2; ++kb)
; #pragma unroll
;                             for (int j = 0; j < 16; ++j) { const int key = 64 * t + 32 * kb + 16 * (j >> 3) + 8 * h + (j & 7); if (key > q) s[kb][j] = -1e30f; }
;                     }
;                     float mx = -1e30f;
; #pragma unroll
;                     for (int kb = 0; kb < 2; ++kb)
; #pragma unroll
;                         for (int j = 0; j < 16; ++j) mx = fmaxf(mx, s[kb][j]);
;                     mx = fmaxf(mx, __shfl_xor(mx, 32));
;                     if (__builtin_amdgcn_ballot_w64(mx > mrun + 8.0f) != 0ull) {
;                         const float mnew = fmaxf(mrun, mx), alpha = fast_exp2(mrun - mnew); mrun = mnew;
;                         lsum *= alpha;
; #pragma unroll
;                         for (int bb = 0; bb < 4; ++bb)
; #pragma unroll
;                             for (int j = 0; j < 16; ++j) o[bb][j] *= alpha;
;                     }
;                     float ps = 0.f;
; #pragma unroll
;                     for (int kb = 0; kb < 2; ++kb)
; #pragma unroll
.Lp2_top1:
	s_waitcnt lgkmcnt(3)
	v_mfma_f32_32x32x16_bf16 v[96:111], v[160:163], v[112:115], v[0:15]
	ds_read_b128 v[160:163], v209 offset:0x10
	v_exp_f32_e32 v228, v228
	v_exp_f32_e32 v229, v229
	s_nop 0
	v_add_f32_e32 v246, v228, v229
	s_waitcnt lgkmcnt(3)
	v_mfma_f32_32x32x16_bf16 v[80:95], v[164:167], v[112:115], v[0:15]
	ds_read_b128 v[164:167], v209 offset:0x3010
	v_cvt_pk_bf16_f32 v228, v228, v229
	v_exp_f32_e32 v230, v230
	v_exp_f32_e32 v231, v231
	s_add_i32 m0, s58, 0xa000
	s_nop 0
	global_load_lds_dwordx4 v176, s[62:63]
	s_waitcnt lgkmcnt(3)
	v_mfma_f32_32x32x16_bf16 v[96:111], v[168:171], v[116:119], v[96:111]
	ds_read_b128 v[168:171], v217 offset:0x10
	v_add_f32_e32 v246, v246, v230
	v_add_f32_e32 v246, v246, v231
	v_cvt_pk_bf16_f32 v229, v230, v231
	v_exp_f32_e32 v232, v232
	s_waitcnt lgkmcnt(3)
	v_mfma_f32_32x32x16_bf16 v[80:95], v[172:175], v[116:119], v[80:95]
	ds_read_b128 v[172:175], v217 offset:0x3010
	v_exp_f32_e32 v233, v233
	v_add_f32_e32 v246, v246, v232
	v_add_f32_e32 v246, v246, v233
	v_cvt_pk_bf16_f32 v230, v232, v233
	s_waitcnt lgkmcnt(3)
	v_mfma_f32_32x32x16_bf16 v[96:111], v[160:163], v[120:123], v[96:111]
	ds_read_b128 v[160:163], v207 offset:0x90
	v_exp_f32_e32 v234, v234
	v_exp_f32_e32 v235, v235
	v_add_f32_e32 v246, v246, v234
	s_waitcnt lgkmcnt(3)
	v_mfma_f32_32x32x16_bf16 v[80:95], v[164:167], v[120:123], v[80:95]
	ds_read_b128 v[164:167], v207 offset:0x3090
	v_add_f32_e32 v246, v246, v235
	v_cvt_pk_bf16_f32 v231, v234, v235
	v_exp_f32_e32 v236, v236
	s_add_i32 m0, s58, 0xc000
	s_nop 0
	global_load_lds_dwordx4 v194, s[62:63]
	s_waitcnt lgkmcnt(3)
	v_mfma_f32_32x32x16_bf16 v[96:111], v[168:171], v[124:127], v[96:111]
	ds_read_b128 v[168:171], v208 offset:0x90
	v_exp_f32_e32 v237, v237
	v_add_f32_e32 v246, v246, v236
	v_add_f32_e32 v246, v246, v237
	v_cvt_pk_bf16_f32 v232, v236, v237
	s_waitcnt lgkmcnt(3)
	v_mfma_f32_32x32x16_bf16 v[80:95], v[172:175], v[124:127], v[80:95]
	ds_read_b128 v[172:175], v208 offset:0x3090
	v_exp_f32_e32 v238, v238
	v_exp_f32_e32 v239, v239
	v_add_f32_e32 v246, v246, v238
	s_waitcnt lgkmcnt(3)
	v_mfma_f32_32x32x16_bf16 v[96:111], v[160:163], v[128:131], v[96:111]
	ds_read_b128 v[160:163], v209 offset:0x90
	v_add_f32_e32 v246, v246, v239
	v_cvt_pk_bf16_f32 v233, v238, v239
	v_exp_f32_e32 v240, v240
	s_waitcnt lgkmcnt(3)
	v_mfma_f32_32x32x16_bf16 v[80:95], v[164:167], v[128:131], v[80:95]
	ds_read_b128 v[164:167], v209 offset:0x3090
	v_exp_f32_e32 v241, v241
	v_add_f32_e32 v246, v246, v240
	v_add_f32_e32 v246, v246, v241
	v_cvt_pk_bf16_f32 v234, v240, v241
	s_add_i32 m0, s58, 0xe000
	s_nop 0
	global_load_lds_dwordx4 v196, s[62:63]
	s_waitcnt lgkmcnt(3)
	v_mfma_f32_32x32x16_bf16 v[96:111], v[168:171], v[132:135], v[96:111]
	ds_read_b128 v[168:171], v217 offset:0x90
	v_exp_f32_e32 v242, v242
	v_exp_f32_e32 v243, v243
	v_add_f32_e32 v246, v246, v242
	s_waitcnt lgkmcnt(3)
	v_mfma_f32_32x32x16_bf16 v[80:95], v[172:175], v[132:135], v[80:95]
	ds_read_b128 v[172:175], v217 offset:0x3090
	v_add_f32_e32 v246, v246, v243
	v_cvt_pk_bf16_f32 v235, v242, v243
	v_exp_f32_e32 v178, v178
	s_waitcnt lgkmcnt(3)
	v_mfma_f32_32x32x16_bf16 v[96:111], v[160:163], v[136:139], v[96:111]
	ds_read_b128 v[160:163], v207 offset:0x110
	v_exp_f32_e32 v179, v179
	v_add_f32_e32 v246, v246, v178
	v_add_f32_e32 v246, v246, v179
	v_cvt_pk_bf16_f32 v178, v178, v179
	s_waitcnt lgkmcnt(3)
	v_mfma_f32_32x32x16_bf16 v[80:95], v[164:167], v[136:139], v[80:95]
	ds_read_b128 v[164:167], v207 offset:0x3110
	v_exp_f32_e32 v180, v180
	v_exp_f32_e32 v181, v181
	v_add_f32_e32 v246, v246, v180
	s_add_i32 m0, s58, 0x6000
	s_nop 0
	global_load_lds_dwordx4 v198, s[72:73]
	s_waitcnt lgkmcnt(3)
	v_mfma_f32_32x32x16_bf16 v[96:111], v[168:171], v[140:143], v[96:111]
	ds_read_b128 v[168:171], v208 offset:0x110
	v_add_f32_e32 v246, v246, v181
	v_cvt_pk_bf16_f32 v179, v180, v181
	v_exp_f32_e32 v182, v182
	s_waitcnt lgkmcnt(3)
	v_mfma_f32_32x32x16_bf16 v[80:95], v[172:175], v[140:143], v[80:95]
	ds_read_b128 v[172:175], v208 offset:0x3110
	v_exp_f32_e32 v183, v183
	v_add_f32_e32 v246, v246, v182
	v_add_f32_e32 v246, v246, v183
	v_cvt_pk_bf16_f32 v180, v182, v183
	s_waitcnt lgkmcnt(3)
	v_mfma_f32_32x32x16_bf16 v[96:111], v[160:163], v[144:147], v[96:111]
	ds_read_b128 v[160:163], v209 offset:0x110
	v_exp_f32_e32 v184, v184
	v_exp_f32_e32 v185, v185
	v_add_f32_e32 v246, v246, v184
	s_waitcnt lgkmcnt(3)
	v_mfma_f32_32x32x16_bf16 v[80:95], v[164:167], v[144:147], v[80:95]
	ds_read_b128 v[164:167], v209 offset:0x3110
	v_add_f32_e32 v246, v246, v185
	v_cvt_pk_bf16_f32 v181, v184, v185
	v_exp_f32_e32 v186, v186
	s_add_i32 m0, s58, 0x8000
	s_nop 0
	global_load_lds_dwordx4 v200, s[72:73]
	s_waitcnt lgkmcnt(3)
	v_mfma_f32_32x32x16_bf16 v[96:111], v[168:171], v[148:151], v[96:111]
	ds_read_b128 v[168:171], v217 offset:0x110
	v_exp_f32_e32 v187, v187
	v_add_f32_e32 v246, v246, v186
	v_add_f32_e32 v246, v246, v187
	v_cvt_pk_bf16_f32 v182, v186, v187
	s_waitcnt lgkmcnt(3)
	v_mfma_f32_32x32x16_bf16 v[80:95], v[172:175], v[148:151], v[80:95]
	ds_read_b128 v[172:175], v217 offset:0x3110
	v_exp_f32_e32 v188, v188
	v_exp_f32_e32 v189, v189
	v_add_f32_e32 v246, v246, v188
	s_waitcnt lgkmcnt(3)
	v_mfma_f32_32x32x16_bf16 v[96:111], v[160:163], v[152:155], v[96:111]
	ds_read_b128 v[160:163], v210 offset:0x8010
	v_add_f32_e32 v246, v246, v189
	v_cvt_pk_bf16_f32 v183, v188, v189
	v_exp_f32_e32 v190, v190
	s_waitcnt lgkmcnt(3)
	v_mfma_f32_32x32x16_bf16 v[80:95], v[164:167], v[152:155], v[80:95]
	ds_read_b128 v[164:167], v210 offset:0x9010
	v_exp_f32_e32 v191, v191
	v_add_f32_e32 v246, v246, v190
	v_add_f32_e32 v246, v246, v191
	v_cvt_pk_bf16_f32 v184, v190, v191
	s_waitcnt lgkmcnt(3)
	v_mfma_f32_32x32x16_bf16 v[96:111], v[168:171], v[156:159], v[96:111]
	ds_read_b128 v[168:171], v210 offset:0xa010
	v_exp_f32_e32 v192, v192
	v_exp_f32_e32 v193, v193
	v_add_f32_e32 v246, v246, v192
	s_waitcnt lgkmcnt(3)
	v_mfma_f32_32x32x16_bf16 v[80:95], v[172:175], v[156:159], v[80:95]
	ds_read_b128 v[172:175], v210 offset:0xb010
	v_add_f32_e32 v246, v246, v193
	v_cvt_pk_bf16_f32 v185, v192, v193
	v_add_f32_e32 v224, v224, v246
	s_waitcnt lgkmcnt(3)
	v_mfma_f32_32x32x16_bf16 v[48:63], v[160:163], v[228:231], v[48:63]
	ds_read_b128 v[160:163], v211 offset:0x8010
	s_waitcnt lgkmcnt(3)
	v_mfma_f32_32x32x16_bf16 v[32:47], v[164:167], v[228:231], v[32:47]
	ds_read_b128 v[164:167], v211 offset:0x9010
	s_waitcnt lgkmcnt(3)
	v_mfma_f32_32x32x16_bf16 v[16:31], v[168:171], v[228:231], v[16:31]
	ds_read_b128 v[168:171], v211 offset:0xa010
	s_waitcnt lgkmcnt(3)
	v_mfma_f32_32x32x16_bf16 v[64:79], v[172:175], v[228:231], v[64:79]
	ds_read_b128 v[172:175], v211 offset:0xb010
	s_cmp_lg_u32 s24, s21
	s_cbranch_scc1 .Lp2_nomask3
; __device__ __forceinline__ void attn_phase(int wv, const bf16_t* Q, const bf16_t* Kf, const bf16_t* Vt, const bf16_t* proj, bf16_t* mixed, LAS unsigned char* lds) { LIDS
;     ...
;                     if (64 * t + 63 > qw0) {
; #pragma unroll
;                         for (int kb = 0; kb < 2; ++kb)
; #pragma unroll
;                             for (int j = 0; j < 16; ++j) { const int key = 64 * t + 32 * kb + 16 * (j >> 3) + 8 * h + (j & 7); if (key > q) s[kb][j] = -1e30f; }
;                     }
	s_lshl_b32 s23, s21, 6
	v_add_u32_e32 v244, s23, v222
	v_sub_u32_e32 v244, v223, v244
	v_cmp_le_i32_e32 vcc, 0, v244
	s_nop 1
	v_cndmask_b32_e32 v96, v215, v96, vcc
	v_cmp_le_i32_e32 vcc, 1, v244
	s_nop 1
	v_cndmask_b32_e32 v97, v215, v97, vcc
	v_cmp_le_i32_e32 vcc, 2, v244
	s_nop 1
	v_cndmask_b32_e32 v98, v215, v98, vcc
	v_cmp_le_i32_e32 vcc, 3, v244
	s_nop 1
	v_cndmask_b32_e32 v99, v215, v99, vcc
	v_cmp_le_i32_e32 vcc, 4, v244
	s_nop 1
	v_cndmask_b32_e32 v100, v215, v100, vcc
	v_cmp_le_i32_e32 vcc, 5, v244
	s_nop 1
	v_cndmask_b32_e32 v101, v215, v101, vcc
	v_cmp_le_i32_e32 vcc, 6, v244
	s_nop 1
	v_cndmask_b32_e32 v102, v215, v102, vcc
	v_cmp_le_i32_e32 vcc, 7, v244
	s_nop 1
	v_cndmask_b32_e32 v103, v215, v103, vcc
	v_cmp_le_i32_e32 vcc, 16, v244
	s_nop 1
	v_cndmask_b32_e32 v104, v215, v104, vcc
	v_cmp_le_i32_e32 vcc, 17, v244
	s_nop 1
	v_cndmask_b32_e32 v105, v215, v105, vcc
	v_cmp_le_i32_e32 vcc, 18, v244
	s_nop 1
	v_cndmask_b32_e32 v106, v215, v106, vcc
	v_cmp_le_i32_e32 vcc, 19, v244
	s_nop 1
	v_cndmask_b32_e32 v107, v215, v107, vcc
	v_cmp_le_i32_e32 vcc, 20, v244
	s_nop 1
	v_cndmask_b32_e32 v108, v215, v108, vcc
	v_cmp_le_i32_e32 vcc, 21, v244
	s_nop 1
	v_cndmask_b32_e32 v109, v215, v109, vcc
	v_cmp_le_i32_e32 vcc, 22, v244
	s_nop 1
	v_cndmask_b32_e32 v110, v215, v110, vcc
	v_cmp_le_i32_e32 vcc, 23, v244
	s_nop 1
	v_cndmask_b32_e32 v111, v215, v111, vcc
	v_cmp_le_i32_e32 vcc, 32, v244
	s_nop 1
	v_cndmask_b32_e32 v80, v215, v80, vcc
	v_cmp_le_i32_e32 vcc, 33, v244
	s_nop 1
	v_cndmask_b32_e32 v81, v215, v81, vcc
	v_cmp_le_i32_e32 vcc, 34, v244
	s_nop 1
	v_cndmask_b32_e32 v82, v215, v82, vcc
	v_cmp_le_i32_e32 vcc, 35, v244
	s_nop 1
	v_cndmask_b32_e32 v83, v215, v83, vcc
	v_cmp_le_i32_e32 vcc, 36, v244
	s_nop 1
	v_cndmask_b32_e32 v84, v215, v84, vcc
	v_cmp_le_i32_e32 vcc, 37, v244
	s_nop 1
	v_cndmask_b32_e32 v85, v215, v85, vcc
	v_cmp_le_i32_e32 vcc, 38, v244
	s_nop 1
	v_cndmask_b32_e32 v86, v215, v86, vcc
	v_cmp_le_i32_e32 vcc, 39, v244
	s_nop 1
	v_cndmask_b32_e32 v87, v215, v87, vcc
	v_cmp_le_i32_e32 vcc, 48, v244
	s_nop 1
	v_cndmask_b32_e32 v88, v215, v88, vcc
	v_cmp_le_i32_e32 vcc, 49, v244
	s_nop 1
	v_cndmask_b32_e32 v89, v215, v89, vcc
	v_cmp_le_i32_e32 vcc, 50, v244
	s_nop 1
	v_cndmask_b32_e32 v90, v215, v90, vcc
	v_cmp_le_i32_e32 vcc, 51, v244
	s_nop 1
	v_cndmask_b32_e32 v91, v215, v91, vcc
	v_cmp_le_i32_e32 vcc, 52, v244
	s_nop 1
	v_cndmask_b32_e32 v92, v215, v92, vcc
	v_cmp_le_i32_e32 vcc, 53, v244
	s_nop 1
	v_cndmask_b32_e32 v93, v215, v93, vcc
	v_cmp_le_i32_e32 vcc, 54, v244
	s_nop 1
	v_cndmask_b32_e32 v94, v215, v94, vcc
	v_cmp_le_i32_e32 vcc, 55, v244
	s_nop 1
	v_cndmask_b32_e32 v95, v215, v95, vcc

; __device__ __forceinline__ unsigned cvt_pk_bf16(float lo, float hi) { unsigned r; asm volatile("v_cvt_pk_bf16_f32 %0, %1, %2" : "=v"(r) : "v"(lo), "v"(hi)); return r; }
; __device__ __forceinline__ float fast_exp2(float x) { return __builtin_amdgcn_exp2f(x); }
; #define LGK(n, f) asm volatile("s_waitcnt lgkmcnt(%1)" : "+v"(f) : "n"(n))
; #define ATT_VRD(j) DSR(fr_[(j) & 3], vad[(j) >> 2], ((j) & 3) * 4096)
; __device__ __forceinline__ void attn_phase(int wv, const bf16_t* Q, const bf16_t* Kf, const bf16_t* Vt, const bf16_t* proj, bf16_t* mixed, LAS unsigned char* lds) { LIDS
;     ...
;             for (int t = 0; t < nt; ++t) {
;                 const int b = t & 1;
;                 asm volatile("s_waitcnt vmcnt(0)" ::: "memory"); __builtin_amdgcn_s_barrier(); asm volatile("" ::: "memory");
;                 if (t + 1 < nt) ATT_ISSUE(t + 1, b ^ 1);
;     ...
;                     float ps = 0.f;
; #pragma unroll
;                     for (int kb = 0; kb < 2; ++kb)
; #pragma unroll
;                         for (int j = 0; j < 16; ++j) { s[kb][j] = fast_exp2(s[kb][j] - mrun); ps += s[kb][j]; }
;                     lsum += ps;
; #pragma unroll
;                     for (int c = 0; c < 4; ++c) {
;                         const int kb = c >> 1, sx = c & 1;
;                         u32x4 pw;
; #pragma unroll
;                         for (int j = 0; j < 4; ++j) pw[j] = cvt_pk_bf16(s[kb][8 * sx + 2 * j], s[kb][8 * sx + 2 * j + 1]);
;                         const bf16x8 pf = __builtin_bit_cast(bf16x8, pw);
; #pragma unroll
;                         for (int bb = 0; bb < 4; ++bb) {
;                             const int j = c * 4 + bb;
;                             LGK(j < 13 ? 3 : 15 - j, fr_[j & 3]);
;                             o[bb] = __builtin_amdgcn_mfma_f32_32x32x16_bf16(fr_[j & 3], pf, o[bb], 0, 0, 0);
;                             if (j + 4 < 16) ATT_VRD(j + 4);
;                         }
;                     }
.Lp2_idle0:
	s_mov_b32 m0, s58
	s_nop 0
	global_load_lds_dwordx4 v176, s[62:63]
	s_add_i32 m0, s58, 0x2000
	s_nop 0
	global_load_lds_dwordx4 v194, s[62:63]
	s_add_i32 m0, s58, 0x4000
	s_nop 0
	global_load_lds_dwordx4 v196, s[62:63]
	s_add_i32 m0, s58, 0x10000
	s_nop 0
	global_load_lds_dwordx4 v198, s[72:73]
	s_add_i32 m0, s58, 0x12000
	s_nop 0
	global_load_lds_dwordx4 v200, s[72:73]
	s_waitcnt vmcnt(0)
	s_barrier
	s_branch .Lp2_tail0
.Lp2_idle1:
	s_add_i32 m0, s58, 0xa000
	s_nop 0
	global_load_lds_dwordx4 v176, s[62:63]
	s_add_i32 m0, s58, 0xc000
	s_nop 0
	global_load_lds_dwordx4 v194, s[62:63]
	s_add_i32 m0, s58, 0xe000
	s_nop 0
	global_load_lds_dwordx4 v196, s[62:63]
	s_add_i32 m0, s58, 0x6000
	s_nop 0
	global_load_lds_dwordx4 v198, s[72:73]
	s_add_i32 m0, s58, 0x8000
	s_nop 0
	global_load_lds_dwordx4 v200, s[72:73]
	s_waitcnt vmcnt(0)
	s_barrier
	s_branch .Lp2_tail1
.Lp2_drain0:
	ds_read_b128 v[160:163], v218 offset:0x6010
	ds_read_b128 v[164:167], v218 offset:0x7010
	ds_read_b128 v[168:171], v218 offset:0x8010
	ds_read_b128 v[172:175], v218 offset:0x9010
	s_mov_b32 m0, s58
	s_nop 0
	global_load_lds_dwordx4 v176, s[62:63]
	s_add_i32 m0, s58, 0x2000
	s_nop 0
	global_load_lds_dwordx4 v194, s[62:63]
	s_add_i32 m0, s58, 0x4000
	s_nop 0
	global_load_lds_dwordx4 v196, s[62:63]
	s_add_i32 m0, s58, 0x10000
	s_nop 0
	global_load_lds_dwordx4 v198, s[72:73]
	s_add_i32 m0, s58, 0x12000
	s_nop 0
	global_load_lds_dwordx4 v200, s[72:73]
	v_exp_f32_e32 v96, v96
	v_exp_f32_e32 v97, v97
	s_nop 0
	v_add_f32_e32 v246, v96, v97
	v_cvt_pk_bf16_f32 v96, v96, v97
	v_exp_f32_e32 v98, v98
	v_exp_f32_e32 v99, v99
	v_add_f32_e32 v246, v246, v98
	v_add_f32_e32 v246, v246, v99
	v_cvt_pk_bf16_f32 v97, v98, v99
	v_exp_f32_e32 v100, v100
	v_exp_f32_e32 v101, v101
	v_add_f32_e32 v246, v246, v100
	v_add_f32_e32 v246, v246, v101
	v_cvt_pk_bf16_f32 v98, v100, v101
	v_exp_f32_e32 v102, v102
	v_exp_f32_e32 v103, v103
	v_add_f32_e32 v246, v246, v102
	v_add_f32_e32 v246, v246, v103
	v_cvt_pk_bf16_f32 v99, v102, v103
	s_waitcnt lgkmcnt(3)
	s_nop 0
	v_mfma_f32_32x32x16_bf16 v[48:63], v[160:163], v[96:99], v[48:63]
	ds_read_b128 v[160:163], v219 offset:0x6010
	v_exp_f32_e32 v104, v104
	v_exp_f32_e32 v105, v105
	v_add_f32_e32 v246, v246, v104
	v_add_f32_e32 v246, v246, v105
	v_cvt_pk_bf16_f32 v100, v104, v105
	s_waitcnt lgkmcnt(3)
	v_mfma_f32_32x32x16_bf16 v[32:47], v[164:167], v[96:99], v[32:47]
	ds_read_b128 v[164:167], v219 offset:0x7010
	v_exp_f32_e32 v106, v106
	v_exp_f32_e32 v107, v107
	v_add_f32_e32 v246, v246, v106
	v_add_f32_e32 v246, v246, v107
	v_cvt_pk_bf16_f32 v101, v106, v107
	s_waitcnt lgkmcnt(3)
	v_mfma_f32_32x32x16_bf16 v[16:31], v[168:171], v[96:99], v[16:31]
	ds_read_b128 v[168:171], v219 offset:0x8010
	v_exp_f32_e32 v108, v108
	v_exp_f32_e32 v109, v109
	v_add_f32_e32 v246, v246, v108
	v_add_f32_e32 v246, v246, v109
	v_cvt_pk_bf16_f32 v102, v108, v109
	s_waitcnt lgkmcnt(3)
	v_mfma_f32_32x32x16_bf16 v[64:79], v[172:175], v[96:99], v[64:79]
	ds_read_b128 v[172:175], v219 offset:0x9010
	v_exp_f32_e32 v110, v110
	v_exp_f32_e32 v111, v111
	v_add_f32_e32 v246, v246, v110
	v_add_f32_e32 v246, v246, v111
	v_cvt_pk_bf16_f32 v103, v110, v111
	s_waitcnt lgkmcnt(3)
	s_nop 0
	v_mfma_f32_32x32x16_bf16 v[48:63], v[160:163], v[100:103], v[48:63]
	ds_read_b128 v[160:163], v220 offset:0x6010
	v_exp_f32_e32 v80, v80
	v_exp_f32_e32 v81, v81
	v_add_f32_e32 v246, v246, v80
	v_add_f32_e32 v246, v246, v81
	v_cvt_pk_bf16_f32 v80, v80, v81
	s_waitcnt lgkmcnt(3)
	v_mfma_f32_32x32x16_bf16 v[32:47], v[164:167], v[100:103], v[32:47]
	ds_read_b128 v[164:167], v220 offset:0x7010
	v_exp_f32_e32 v82, v82
	v_exp_f32_e32 v83, v83
	v_add_f32_e32 v246, v246, v82
	v_add_f32_e32 v246, v246, v83
	v_cvt_pk_bf16_f32 v81, v82, v83
	s_waitcnt lgkmcnt(3)
	v_mfma_f32_32x32x16_bf16 v[16:31], v[168:171], v[100:103], v[16:31]
	ds_read_b128 v[168:171], v220 offset:0x8010
	v_exp_f32_e32 v84, v84
	v_exp_f32_e32 v85, v85
	v_add_f32_e32 v246, v246, v84
	v_add_f32_e32 v246, v246, v85
	v_cvt_pk_bf16_f32 v82, v84, v85
	s_waitcnt lgkmcnt(3)
	v_mfma_f32_32x32x16_bf16 v[64:79], v[172:175], v[100:103], v[64:79]
	ds_read_b128 v[172:175], v220 offset:0x9010
	v_exp_f32_e32 v86, v86
	v_exp_f32_e32 v87, v87
	v_add_f32_e32 v246, v246, v86
	v_add_f32_e32 v246, v246, v87
	v_cvt_pk_bf16_f32 v83, v86, v87
	s_waitcnt lgkmcnt(3)
	s_nop 0
	v_mfma_f32_32x32x16_bf16 v[48:63], v[160:163], v[80:83], v[48:63]
	ds_read_b128 v[160:163], v221 offset:0x6010
	v_exp_f32_e32 v88, v88
	v_exp_f32_e32 v89, v89
	v_add_f32_e32 v246, v246, v88
	v_add_f32_e32 v246, v246, v89
	v_cvt_pk_bf16_f32 v84, v88, v89
	s_waitcnt lgkmcnt(3)
	v_mfma_f32_32x32x16_bf16 v[32:47], v[164:167], v[80:83], v[32:47]
	ds_read_b128 v[164:167], v221 offset:0x7010
	v_exp_f32_e32 v90, v90
	v_exp_f32_e32 v91, v91
	v_add_f32_e32 v246, v246, v90
	v_add_f32_e32 v246, v246, v91
	v_cvt_pk_bf16_f32 v85, v90, v91
	s_waitcnt lgkmcnt(3)
	v_mfma_f32_32x32x16_bf16 v[16:31], v[168:171], v[80:83], v[16:31]
	ds_read_b128 v[168:171], v221 offset:0x8010
	v_exp_f32_e32 v92, v92
	v_exp_f32_e32 v93, v93
	v_add_f32_e32 v246, v246, v92
	v_add_f32_e32 v246, v246, v93
	v_cvt_pk_bf16_f32 v86, v92, v93
	s_waitcnt lgkmcnt(3)
	v_mfma_f32_32x32x16_bf16 v[64:79], v[172:175], v[80:83], v[64:79]
	ds_read_b128 v[172:175], v221 offset:0x9010
	v_exp_f32_e32 v94, v94
	v_exp_f32_e32 v95, v95
	v_add_f32_e32 v246, v246, v94
	v_add_f32_e32 v246, v246, v95
	v_cvt_pk_bf16_f32 v87, v94, v95
	s_waitcnt lgkmcnt(3)
	s_nop 0
	v_mfma_f32_32x32x16_bf16 v[48:63], v[160:163], v[84:87], v[48:63]
	v_add_f32_e32 v224, v224, v246
	s_waitcnt lgkmcnt(2)
	v_mfma_f32_32x32x16_bf16 v[32:47], v[164:167], v[84:87], v[32:47]
	s_waitcnt lgkmcnt(1)
	v_mfma_f32_32x32x16_bf16 v[16:31], v[168:171], v[84:87], v[16:31]
	s_waitcnt lgkmcnt(0)
	v_mfma_f32_32x32x16_bf16 v[64:79], v[172:175], v[84:87], v[64:79]
	s_waitcnt lgkmcnt(0)
	s_waitcnt vmcnt(0)
	s_barrier
	s_branch .Lp2_tail0
; __device__ __forceinline__ unsigned cvt_pk_bf16(float lo, float hi) { unsigned r; asm volatile("v_cvt_pk_bf16_f32 %0, %1, %2" : "=v"(r) : "v"(lo), "v"(hi)); return r; }
; __device__ __forceinline__ float fast_exp2(float x) { return __builtin_amdgcn_exp2f(x); }
; #define LGK(n, f) asm volatile("s_waitcnt lgkmcnt(%1)" : "+v"(f) : "n"(n))
; #define ATT_VRD(j) DSR(fr_[(j) & 3], vad[(j) >> 2], ((j) & 3) * 4096)
; __device__ __forceinline__ void attn_phase(int wv, const bf16_t* Q, const bf16_t* Kf, const bf16_t* Vt, const bf16_t* proj, bf16_t* mixed, LAS unsigned char* lds) { LIDS
;     ...
;             for (int t = 0; t < nt; ++t) {
;                 const int b = t & 1;
;                 asm volatile("s_waitcnt vmcnt(0)" ::: "memory"); __builtin_amdgcn_s_barrier(); asm volatile("" ::: "memory");
;                 if (t + 1 < nt) ATT_ISSUE(t + 1, b ^ 1);
;     ...
;                     float ps = 0.f;
; #pragma unroll
;                     for (int kb = 0; kb < 2; ++kb)
; #pragma unroll
;                         for (int j = 0; j < 16; ++j) { s[kb][j] = fast_exp2(s[kb][j] - mrun); ps += s[kb][j]; }
;                     lsum += ps;
; #pragma unroll
;                     for (int c = 0; c < 4; ++c) {
;                         const int kb = c >> 1, sx = c & 1;
;                         u32x4 pw;
; #pragma unroll
;                         for (int j = 0; j < 4; ++j) pw[j] = cvt_pk_bf16(s[kb][8 * sx + 2 * j], s[kb][8 * sx + 2 * j + 1]);
;                         const bf16x8 pf = __builtin_bit_cast(bf16x8, pw);
; #pragma unroll
;                         for (int bb = 0; bb < 4; ++bb) {
;                             const int j = c * 4 + bb;
;                             LGK(j < 13 ? 3 : 15 - j, fr_[j & 3]);
;                             o[bb] = __builtin_amdgcn_mfma_f32_32x32x16_bf16(fr_[j & 3], pf, o[bb], 0, 0, 0);
;                             if (j + 4 < 16) ATT_VRD(j + 4);
;                         }
;                     }
.Lp2_drain1:
	ds_read_b128 v[160:163], v210 offset:0x8010
	ds_read_b128 v[164:167], v210 offset:0x9010
	ds_read_b128 v[168:171], v210 offset:0xa010
	ds_read_b128 v[172:175], v210 offset:0xb010
	s_add_i32 m0, s58, 0xa000
	s_nop 0
	global_load_lds_dwordx4 v176, s[62:63]
	s_add_i32 m0, s58, 0xc000
	s_nop 0
	global_load_lds_dwordx4 v194, s[62:63]
	s_add_i32 m0, s58, 0xe000
	s_nop 0
	global_load_lds_dwordx4 v196, s[62:63]
	s_add_i32 m0, s58, 0x6000
	s_nop 0
	global_load_lds_dwordx4 v198, s[72:73]
	s_add_i32 m0, s58, 0x8000
	s_nop 0
	global_load_lds_dwordx4 v200, s[72:73]
	v_exp_f32_e32 v228, v228
	v_exp_f32_e32 v229, v229
	s_nop 0
	v_add_f32_e32 v246, v228, v229
	v_cvt_pk_bf16_f32 v228, v228, v229
	v_exp_f32_e32 v230, v230
	v_exp_f32_e32 v231, v231
	v_add_f32_e32 v246, v246, v230
	v_add_f32_e32 v246, v246, v231
	v_cvt_pk_bf16_f32 v229, v230, v231
	v_exp_f32_e32 v232, v232
	v_exp_f32_e32 v233, v233
	v_add_f32_e32 v246, v246, v232
	v_add_f32_e32 v246, v246, v233
	v_cvt_pk_bf16_f32 v230, v232, v233
	v_exp_f32_e32 v234, v234
	v_exp_f32_e32 v235, v235
	v_add_f32_e32 v246, v246, v234
	v_add_f32_e32 v246, v246, v235
	v_cvt_pk_bf16_f32 v231, v234, v235
	s_waitcnt lgkmcnt(3)
	s_nop 0
	v_mfma_f32_32x32x16_bf16 v[48:63], v[160:163], v[228:231], v[48:63]
	ds_read_b128 v[160:163], v211 offset:0x8010
	v_exp_f32_e32 v236, v236
	v_exp_f32_e32 v237, v237
	v_add_f32_e32 v246, v246, v236
	v_add_f32_e32 v246, v246, v237
	v_cvt_pk_bf16_f32 v232, v236, v237
	s_waitcnt lgkmcnt(3)
	v_mfma_f32_32x32x16_bf16 v[32:47], v[164:167], v[228:231], v[32:47]
	ds_read_b128 v[164:167], v211 offset:0x9010
	v_exp_f32_e32 v238, v238
	v_exp_f32_e32 v239, v239
	v_add_f32_e32 v246, v246, v238
	v_add_f32_e32 v246, v246, v239
	v_cvt_pk_bf16_f32 v233, v238, v239
	s_waitcnt lgkmcnt(3)
	v_mfma_f32_32x32x16_bf16 v[16:31], v[168:171], v[228:231], v[16:31]
	ds_read_b128 v[168:171], v211 offset:0xa010
	v_exp_f32_e32 v240, v240
	v_exp_f32_e32 v241, v241
	v_add_f32_e32 v246, v246, v240
	v_add_f32_e32 v246, v246, v241
	v_cvt_pk_bf16_f32 v234, v240, v241
	s_waitcnt lgkmcnt(3)
	v_mfma_f32_32x32x16_bf16 v[64:79], v[172:175], v[228:231], v[64:79]
	ds_read_b128 v[172:175], v211 offset:0xb010
	v_exp_f32_e32 v242, v242
	v_exp_f32_e32 v243, v243
	v_add_f32_e32 v246, v246, v242
	v_add_f32_e32 v246, v246, v243
	v_cvt_pk_bf16_f32 v235, v242, v243
	s_waitcnt lgkmcnt(3)
	s_nop 0
	v_mfma_f32_32x32x16_bf16 v[48:63], v[160:163], v[232:235], v[48:63]
	ds_read_b128 v[160:163], v212 offset:0x8010
	v_exp_f32_e32 v178, v178
	v_exp_f32_e32 v179, v179
	v_add_f32_e32 v246, v246, v178
	v_add_f32_e32 v246, v246, v179
	v_cvt_pk_bf16_f32 v178, v178, v179
	s_waitcnt lgkmcnt(3)
	v_mfma_f32_32x32x16_bf16 v[32:47], v[164:167], v[232:235], v[32:47]
	ds_read_b128 v[164:167], v212 offset:0x9010
	v_exp_f32_e32 v180, v180
	v_exp_f32_e32 v181, v181
	v_add_f32_e32 v246, v246, v180
	v_add_f32_e32 v246, v246, v181
	v_cvt_pk_bf16_f32 v179, v180, v181
	s_waitcnt lgkmcnt(3)
	v_mfma_f32_32x32x16_bf16 v[16:31], v[168:171], v[232:235], v[16:31]
	ds_read_b128 v[168:171], v212 offset:0xa010
	v_exp_f32_e32 v182, v182
	v_exp_f32_e32 v183, v183
	v_add_f32_e32 v246, v246, v182
	v_add_f32_e32 v246, v246, v183
	v_cvt_pk_bf16_f32 v180, v182, v183
	s_waitcnt lgkmcnt(3)
	v_mfma_f32_32x32x16_bf16 v[64:79], v[172:175], v[232:235], v[64:79]
	ds_read_b128 v[172:175], v212 offset:0xb010
	v_exp_f32_e32 v184, v184
	v_exp_f32_e32 v185, v185
	v_add_f32_e32 v246, v246, v184
	v_add_f32_e32 v246, v246, v185
	v_cvt_pk_bf16_f32 v181, v184, v185
	s_waitcnt lgkmcnt(3)
	s_nop 0
	v_mfma_f32_32x32x16_bf16 v[48:63], v[160:163], v[178:181], v[48:63]
	ds_read_b128 v[160:163], v213 offset:0x8010
	v_exp_f32_e32 v186, v186
	v_exp_f32_e32 v187, v187
	v_add_f32_e32 v246, v246, v186
	v_add_f32_e32 v246, v246, v187
	v_cvt_pk_bf16_f32 v182, v186, v187
	s_waitcnt lgkmcnt(3)
	v_mfma_f32_32x32x16_bf16 v[32:47], v[164:167], v[178:181], v[32:47]
	ds_read_b128 v[164:167], v213 offset:0x9010
	v_exp_f32_e32 v188, v188
	v_exp_f32_e32 v189, v189
	v_add_f32_e32 v246, v246, v188
	v_add_f32_e32 v246, v246, v189
	v_cvt_pk_bf16_f32 v183, v188, v189
	s_waitcnt lgkmcnt(3)
	v_mfma_f32_32x32x16_bf16 v[16:31], v[168:171], v[178:181], v[16:31]
	ds_read_b128 v[168:171], v213 offset:0xa010
	v_exp_f32_e32 v190, v190
	v_exp_f32_e32 v191, v191
	v_add_f32_e32 v246, v246, v190
	v_add_f32_e32 v246, v246, v191
	v_cvt_pk_bf16_f32 v184, v190, v191
	s_waitcnt lgkmcnt(3)
	v_mfma_f32_32x32x16_bf16 v[64:79], v[172:175], v[178:181], v[64:79]
	ds_read_b128 v[172:175], v213 offset:0xb010
	v_exp_f32_e32 v192, v192
	v_exp_f32_e32 v193, v193
	v_add_f32_e32 v246, v246, v192
	v_add_f32_e32 v246, v246, v193
	v_cvt_pk_bf16_f32 v185, v192, v193
	s_waitcnt lgkmcnt(3)
	s_nop 0
	v_mfma_f32_32x32x16_bf16 v[48:63], v[160:163], v[182:185], v[48:63]
	v_add_f32_e32 v224, v224, v246
	s_waitcnt lgkmcnt(2)
	v_mfma_f32_32x32x16_bf16 v[32:47], v[164:167], v[182:185], v[32:47]
	s_waitcnt lgkmcnt(1)
	v_mfma_f32_32x32x16_bf16 v[16:31], v[168:171], v[182:185], v[16:31]
	s_waitcnt lgkmcnt(0)
	v_mfma_f32_32x32x16_bf16 v[64:79], v[172:175], v[182:185], v[64:79]
	s_waitcnt lgkmcnt(0)
	s_waitcnt vmcnt(0)
	s_barrier
	s_branch .Lp2_tail1
